# out-proj and FF2 residual epilogues rewritten as rolling pipelines (gate quads loaded once per tile, x rows streamed through 3 buffers with counted waits), plus FF1 paired 16-byte stores and unrolled
# speedup vs baseline: 1.0280x; 1.0106x over previous
;     __device__ __forceinline__ void fin(int m, int n, f32x4 v, f32x4, f32x4) const { horiz(m, n, v); }
;     __device__ __forceinline__ void fin(int m, int n, f32x4 v, f32x4, f32x4) const { horiz(m, n, v); }
; template <int MI, bool SWAP, class Epi> ...
;     ...
;     if (SWAP) {
; #pragma unroll
;         for (int i2 = 0; i2 < MI / 2; ++i2) {
;             f32x4 pa[2][4], pg[2][4];
; #pragma unroll
;             for (int ii = 0; ii < 2; ++ii)
; #pragma unroll
;                 for (int j = 0; j < 4; ++j) epi.pre(m0 + wr * (MI * 16) + (i2 * 2 + ii) * 16 + fr, n0 + wc * 64 + j * 16 + fq * 4, pa[ii][j], pg[ii][j]);
;             __builtin_amdgcn_sched_barrier(0);
; #pragma unroll
;             for (int ii = 0; ii < 2; ++ii)
; #pragma unroll
;                 for (int j = 0; j < 4; ++j) epi.fin(m0 + wr * (MI * 16) + (i2 * 2 + ii) * 16 + fr, n0 + wc * 64 + j * 16 + fq * 4, acc[i2 * 2 + ii][j], pa[ii][j], pg[ii][j]);
;         }
.LBB0_1990:
	v_or_b32_e32 v128, s22, v221
	v_add_u32_e32 v130, s26, v128
	v_lshl_or_b32 v128, v218, 2, s11
	v_or_b32_e32 v128, s27, v128
	s_mov_b32 s4, 0x8000
	v_readlane_b32 s6, v252, 20
	v_readlane_b32 s0, v252, 18
	v_readlane_b32 s7, v252, 21
	v_readlane_b32 s1, v252, 19
	v_readlane_b32 s24, v248, 47
	v_readlane_b32 s26, v248, 49
	v_readlane_b32 s27, v248, 50
	v_readlane_b32 s5, v250, 4
	v_readlane_b32 s25, v248, 48
	v_readlane_b32 s28, v248, 51
	v_readlane_b32 s29, v248, 52
	v_readlane_b32 s30, v248, 53
	v_readlane_b32 s31, v248, 54
	v_ashrrev_i32_e32 v129, 31, v128
	v_lshlrev_b64 v[128:129], 2, v[128:129]
	v_min_i32_e32 v131, 0x8000, v130
	v_ashrrev_i32_e32 v131, 11, v131
	v_mul_hi_i32_i24_e32 v133, 0x6000, v131
	v_mul_i32_i24_e32 v132, 0x6000, v131
	v_lshl_add_u64 v[132:133], s[14:15], 0, v[132:133]
	v_lshl_add_u64 v[132:133], v[132:133], 0, v[128:129]
	v_mov_b32_e32 v131, 0
	v_lshlrev_b64 v[130:131], 12, v[130:131]
	v_lshl_add_u64 v[134:135], s[0:1], 0, v[130:131]
	v_lshl_add_u64 v[134:135], v[134:135], 0, v[128:129]
	v_lshl_add_u64 v[136:137], s[26:27], 0, v[130:131]
	v_lshl_add_u64 v[136:137], v[136:137], 0, v[128:129]
	s_mov_b64 vcc, 0x10000
	global_load_dwordx4 v[140:143], v[132:133], off
	global_load_dwordx4 v[144:147], v[132:133], off offset:64
	global_load_dwordx4 v[148:151], v[132:133], off offset:128
	global_load_dwordx4 v[152:155], v[132:133], off offset:192
	global_load_dwordx4 v[156:159], v[134:135], off
	global_load_dwordx4 v[160:163], v[134:135], off offset:64
	global_load_dwordx4 v[164:167], v[134:135], off offset:128
	global_load_dwordx4 v[168:171], v[134:135], off offset:192
	s_nop 0
	v_lshl_add_u64 v[134:135], v[134:135], 0, vcc
	global_load_dwordx4 v[172:175], v[134:135], off
	global_load_dwordx4 v[176:179], v[134:135], off offset:64
	global_load_dwordx4 v[220:223], v[134:135], off offset:128
	global_load_dwordx4 v[224:227], v[134:135], off offset:192
	s_nop 0
	v_lshl_add_u64 v[134:135], v[134:135], 0, vcc
	global_load_dwordx4 v[228:231], v[134:135], off
	global_load_dwordx4 v[232:235], v[134:135], off offset:64
	global_load_dwordx4 v[236:239], v[134:135], off offset:128
	global_load_dwordx4 v[240:243], v[134:135], off offset:192
	s_nop 0
	v_lshl_add_u64 v[134:135], v[134:135], 0, vcc
	s_waitcnt vmcnt(8)
	v_pk_fma_f32 v[124:125], v[124:125], v[140:141], v[156:157]
	v_pk_fma_f32 v[126:127], v[126:127], v[142:143], v[158:159]
	v_pk_fma_f32 v[120:121], v[120:121], v[144:145], v[160:161]
	v_pk_fma_f32 v[122:123], v[122:123], v[146:147], v[162:163]
	v_pk_fma_f32 v[116:117], v[116:117], v[148:149], v[164:165]
	v_pk_fma_f32 v[118:119], v[118:119], v[150:151], v[166:167]
	v_pk_fma_f32 v[112:113], v[112:113], v[152:153], v[168:169]
	v_pk_fma_f32 v[114:115], v[114:115], v[154:155], v[170:171]
	global_store_dwordx4 v[136:137], v[124:127], off
	global_store_dwordx4 v[136:137], v[120:123], off offset:64
	global_store_dwordx4 v[136:137], v[116:119], off offset:128
	global_store_dwordx4 v[136:137], v[112:115], off offset:192
	s_nop 0
	v_lshl_add_u64 v[136:137], v[136:137], 0, vcc
	global_load_dwordx4 v[156:159], v[134:135], off
	global_load_dwordx4 v[160:163], v[134:135], off offset:64
	global_load_dwordx4 v[164:167], v[134:135], off offset:128
	global_load_dwordx4 v[168:171], v[134:135], off offset:192
	s_nop 0
	v_lshl_add_u64 v[134:135], v[134:135], 0, vcc
	s_waitcnt vmcnt(12)
	v_pk_fma_f32 v[108:109], v[108:109], v[140:141], v[172:173]
	v_pk_fma_f32 v[110:111], v[110:111], v[142:143], v[174:175]
	v_pk_fma_f32 v[104:105], v[104:105], v[144:145], v[176:177]
	v_pk_fma_f32 v[106:107], v[106:107], v[146:147], v[178:179]
	v_pk_fma_f32 v[100:101], v[100:101], v[148:149], v[220:221]
	v_pk_fma_f32 v[102:103], v[102:103], v[150:151], v[222:223]
	v_pk_fma_f32 v[96:97], v[96:97], v[152:153], v[224:225]
	v_pk_fma_f32 v[98:99], v[98:99], v[154:155], v[226:227]
	global_store_dwordx4 v[136:137], v[108:111], off
	global_store_dwordx4 v[136:137], v[104:107], off offset:64
	global_store_dwordx4 v[136:137], v[100:103], off offset:128
	global_store_dwordx4 v[136:137], v[96:99], off offset:192
	s_nop 0
	v_lshl_add_u64 v[136:137], v[136:137], 0, vcc
	global_load_dwordx4 v[172:175], v[134:135], off
	global_load_dwordx4 v[176:179], v[134:135], off offset:64
	global_load_dwordx4 v[220:223], v[134:135], off offset:128
	global_load_dwordx4 v[224:227], v[134:135], off offset:192
	s_nop 0
	v_lshl_add_u64 v[134:135], v[134:135], 0, vcc
	s_waitcnt vmcnt(16)
;     __device__ __forceinline__ void fin(int m, int n, f32x4 v, f32x4, f32x4) const { horiz(m, n, v); }
;     __device__ __forceinline__ void fin(int m, int n, f32x4 v, f32x4, f32x4) const { horiz(m, n, v); }
; template <int MI, bool SWAP, class Epi> ...
;     ...
;     if (SWAP) {
; #pragma unroll
;         for (int i2 = 0; i2 < MI / 2; ++i2) {
;             f32x4 pa[2][4], pg[2][4];
; #pragma unroll
;             for (int ii = 0; ii < 2; ++ii)
; #pragma unroll
;                 for (int j = 0; j < 4; ++j) epi.pre(m0 + wr * (MI * 16) + (i2 * 2 + ii) * 16 + fr, n0 + wc * 64 + j * 16 + fq * 4, pa[ii][j], pg[ii][j]);
;             __builtin_amdgcn_sched_barrier(0);
; #pragma unroll
;             for (int ii = 0; ii < 2; ++ii)
; #pragma unroll
;                 for (int j = 0; j < 4; ++j) epi.fin(m0 + wr * (MI * 16) + (i2 * 2 + ii) * 16 + fr, n0 + wc * 64 + j * 16 + fq * 4, acc[i2 * 2 + ii][j], pa[ii][j], pg[ii][j]);
;         }
	v_pk_fma_f32 v[92:93], v[92:93], v[140:141], v[228:229]
	v_pk_fma_f32 v[94:95], v[94:95], v[142:143], v[230:231]
	v_pk_fma_f32 v[88:89], v[88:89], v[144:145], v[232:233]
	v_pk_fma_f32 v[90:91], v[90:91], v[146:147], v[234:235]
	v_pk_fma_f32 v[84:85], v[84:85], v[148:149], v[236:237]
	v_pk_fma_f32 v[86:87], v[86:87], v[150:151], v[238:239]
	v_pk_fma_f32 v[80:81], v[80:81], v[152:153], v[240:241]
	v_pk_fma_f32 v[82:83], v[82:83], v[154:155], v[242:243]
	global_store_dwordx4 v[136:137], v[92:95], off
	global_store_dwordx4 v[136:137], v[88:91], off offset:64
	global_store_dwordx4 v[136:137], v[84:87], off offset:128
	global_store_dwordx4 v[136:137], v[80:83], off offset:192
	s_nop 0
	v_lshl_add_u64 v[136:137], v[136:137], 0, vcc
	global_load_dwordx4 v[228:231], v[134:135], off
	global_load_dwordx4 v[232:235], v[134:135], off offset:64
	global_load_dwordx4 v[236:239], v[134:135], off offset:128
	global_load_dwordx4 v[240:243], v[134:135], off offset:192
	s_nop 0
	v_lshl_add_u64 v[134:135], v[134:135], 0, vcc
	s_waitcnt vmcnt(16)
	v_pk_fma_f32 v[76:77], v[76:77], v[140:141], v[156:157]
	v_pk_fma_f32 v[78:79], v[78:79], v[142:143], v[158:159]
	v_pk_fma_f32 v[72:73], v[72:73], v[144:145], v[160:161]
	v_pk_fma_f32 v[74:75], v[74:75], v[146:147], v[162:163]
	v_pk_fma_f32 v[68:69], v[68:69], v[148:149], v[164:165]
	v_pk_fma_f32 v[70:71], v[70:71], v[150:151], v[166:167]
	v_pk_fma_f32 v[64:65], v[64:65], v[152:153], v[168:169]
	v_pk_fma_f32 v[66:67], v[66:67], v[154:155], v[170:171]
	global_store_dwordx4 v[136:137], v[76:79], off
	global_store_dwordx4 v[136:137], v[72:75], off offset:64
	global_store_dwordx4 v[136:137], v[68:71], off offset:128
	global_store_dwordx4 v[136:137], v[64:67], off offset:192
	s_nop 0
	v_lshl_add_u64 v[136:137], v[136:137], 0, vcc
	global_load_dwordx4 v[156:159], v[134:135], off
	global_load_dwordx4 v[160:163], v[134:135], off offset:64
	global_load_dwordx4 v[164:167], v[134:135], off offset:128
	global_load_dwordx4 v[168:171], v[134:135], off offset:192
	s_nop 0
	v_lshl_add_u64 v[134:135], v[134:135], 0, vcc
	s_waitcnt vmcnt(16)
	v_pk_fma_f32 v[60:61], v[60:61], v[140:141], v[172:173]
	v_pk_fma_f32 v[62:63], v[62:63], v[142:143], v[174:175]
	v_pk_fma_f32 v[56:57], v[56:57], v[144:145], v[176:177]
	v_pk_fma_f32 v[58:59], v[58:59], v[146:147], v[178:179]
	v_pk_fma_f32 v[52:53], v[52:53], v[148:149], v[220:221]
	v_pk_fma_f32 v[54:55], v[54:55], v[150:151], v[222:223]
	v_pk_fma_f32 v[48:49], v[48:49], v[152:153], v[224:225]
	v_pk_fma_f32 v[50:51], v[50:51], v[154:155], v[226:227]
	global_store_dwordx4 v[136:137], v[60:63], off
	global_store_dwordx4 v[136:137], v[56:59], off offset:64
	global_store_dwordx4 v[136:137], v[52:55], off offset:128
	global_store_dwordx4 v[136:137], v[48:51], off offset:192
	s_nop 0
	v_lshl_add_u64 v[136:137], v[136:137], 0, vcc
	global_load_dwordx4 v[172:175], v[134:135], off
	global_load_dwordx4 v[176:179], v[134:135], off offset:64
	global_load_dwordx4 v[220:223], v[134:135], off offset:128
	global_load_dwordx4 v[224:227], v[134:135], off offset:192
	s_waitcnt vmcnt(16)
	v_pk_fma_f32 v[44:45], v[44:45], v[140:141], v[228:229]
	v_pk_fma_f32 v[46:47], v[46:47], v[142:143], v[230:231]
	v_pk_fma_f32 v[40:41], v[40:41], v[144:145], v[232:233]
	v_pk_fma_f32 v[42:43], v[42:43], v[146:147], v[234:235]
	v_pk_fma_f32 v[36:37], v[36:37], v[148:149], v[236:237]
	v_pk_fma_f32 v[38:39], v[38:39], v[150:151], v[238:239]
	v_pk_fma_f32 v[32:33], v[32:33], v[152:153], v[240:241]
	v_pk_fma_f32 v[34:35], v[34:35], v[154:155], v[242:243]
	global_store_dwordx4 v[136:137], v[44:47], off
	global_store_dwordx4 v[136:137], v[40:43], off offset:64
	global_store_dwordx4 v[136:137], v[36:39], off offset:128
	global_store_dwordx4 v[136:137], v[32:35], off offset:192
	s_nop 0
	v_lshl_add_u64 v[136:137], v[136:137], 0, vcc
	s_waitcnt vmcnt(12)
	v_pk_fma_f32 v[28:29], v[28:29], v[140:141], v[156:157]
	v_pk_fma_f32 v[30:31], v[30:31], v[142:143], v[158:159]
	v_pk_fma_f32 v[24:25], v[24:25], v[144:145], v[160:161]
	v_pk_fma_f32 v[26:27], v[26:27], v[146:147], v[162:163]
	v_pk_fma_f32 v[20:21], v[20:21], v[148:149], v[164:165]
	v_pk_fma_f32 v[22:23], v[22:23], v[150:151], v[166:167]
	v_pk_fma_f32 v[16:17], v[16:17], v[152:153], v[168:169]
	v_pk_fma_f32 v[18:19], v[18:19], v[154:155], v[170:171]
	global_store_dwordx4 v[136:137], v[28:31], off
	global_store_dwordx4 v[136:137], v[24:27], off offset:64
	global_store_dwordx4 v[136:137], v[20:23], off offset:128
	global_store_dwordx4 v[136:137], v[16:19], off offset:192
	s_nop 0
	v_lshl_add_u64 v[136:137], v[136:137], 0, vcc
	s_waitcnt vmcnt(8)
	v_pk_fma_f32 v[12:13], v[12:13], v[140:141], v[172:173]
	v_pk_fma_f32 v[14:15], v[14:15], v[142:143], v[174:175]
	v_pk_fma_f32 v[8:9], v[8:9], v[144:145], v[176:177]
	v_pk_fma_f32 v[10:11], v[10:11], v[146:147], v[178:179]
	v_pk_fma_f32 v[4:5], v[4:5], v[148:149], v[220:221]
	v_pk_fma_f32 v[6:7], v[6:7], v[150:151], v[222:223]
	v_pk_fma_f32 v[0:1], v[0:1], v[152:153], v[224:225]
	v_pk_fma_f32 v[2:3], v[2:3], v[154:155], v[226:227]
	global_store_dwordx4 v[136:137], v[12:15], off
	global_store_dwordx4 v[136:137], v[8:11], off offset:64
	global_store_dwordx4 v[136:137], v[4:7], off offset:128
	global_store_dwordx4 v[136:137], v[0:3], off offset:192
	s_andn2_b64 vcc, exec, s[2:3]
	s_mov_b64 s[22:23], -1
	s_cbranch_vccz .LBB0_1992
	s_mov_b32 s72, s10
	s_mov_b32 s70, s18
	s_branch .LBB0_1947

;     __device__ __forceinline__ void fin(int m, int n, f32x4 v, f32x4, f32x4) const { horiz(m, n, v); }
;     __device__ __forceinline__ void fin(int m, int n, f32x4 v, f32x4, f32x4) const { horiz(m, n, v); }
; template <int MI, bool SWAP, class Epi> ...
;     ...
;     if (SWAP) {
; #pragma unroll
;         for (int i2 = 0; i2 < MI / 2; ++i2) {
;             f32x4 pa[2][4], pg[2][4];
; #pragma unroll
;             for (int ii = 0; ii < 2; ++ii)
; #pragma unroll
;                 for (int j = 0; j < 4; ++j) epi.pre(m0 + wr * (MI * 16) + (i2 * 2 + ii) * 16 + fr, n0 + wc * 64 + j * 16 + fq * 4, pa[ii][j], pg[ii][j]);
;             __builtin_amdgcn_sched_barrier(0);
; #pragma unroll
;             for (int ii = 0; ii < 2; ++ii)
; #pragma unroll
;                 for (int j = 0; j < 4; ++j) epi.fin(m0 + wr * (MI * 16) + (i2 * 2 + ii) * 16 + fr, n0 + wc * 64 + j * 16 + fq * 4, acc[i2 * 2 + ii][j], pa[ii][j], pg[ii][j]);
;         }
.LBB0_2322:
	v_or_b32_e32 v128, s24, v221
	v_add_u32_e32 v130, s28, v128
	v_lshl_or_b32 v128, v218, 2, s11
	v_or_b32_e32 v128, s29, v128
	s_mov_b32 s0, 0x8000
	v_readlane_b32 s24, v248, 47
	v_readlane_b32 s26, v248, 49
	v_readlane_b32 s27, v248, 50
	v_readlane_b32 s1, v250, 4
	v_readlane_b32 s25, v248, 48
	v_readlane_b32 s28, v248, 51
	v_readlane_b32 s29, v248, 52
	v_readlane_b32 s30, v248, 53
	v_readlane_b32 s31, v248, 54
	v_ashrrev_i32_e32 v129, 31, v128
	v_lshlrev_b64 v[128:129], 2, v[128:129]
	v_min_i32_e32 v131, 0x8000, v130
	v_ashrrev_i32_e32 v131, 11, v131
	v_mul_hi_i32_i24_e32 v133, 0x6000, v131
	v_mul_i32_i24_e32 v132, 0x6000, v131
	v_lshl_add_u64 v[132:133], s[16:17], 0, v[132:133]
	v_lshl_add_u64 v[132:133], v[132:133], 0, v[128:129]
	v_mov_b32_e32 v131, 0
	v_lshlrev_b64 v[130:131], 12, v[130:131]
	v_lshl_add_u64 v[134:135], s[26:27], 0, v[130:131]
	v_lshl_add_u64 v[134:135], v[134:135], 0, v[128:129]
	v_lshl_add_u64 v[136:137], s[26:27], 0, v[130:131]
	v_lshl_add_u64 v[136:137], v[136:137], 0, v[128:129]
	s_mov_b64 vcc, 0x10000
	global_load_dwordx4 v[140:143], v[132:133], off
	global_load_dwordx4 v[144:147], v[132:133], off offset:64
	global_load_dwordx4 v[148:151], v[132:133], off offset:128
	global_load_dwordx4 v[152:155], v[132:133], off offset:192
	global_load_dwordx4 v[156:159], v[134:135], off
	global_load_dwordx4 v[160:163], v[134:135], off offset:64
	global_load_dwordx4 v[164:167], v[134:135], off offset:128
	global_load_dwordx4 v[168:171], v[134:135], off offset:192
	s_nop 0
	v_lshl_add_u64 v[134:135], v[134:135], 0, vcc
	global_load_dwordx4 v[172:175], v[134:135], off
	global_load_dwordx4 v[176:179], v[134:135], off offset:64
	global_load_dwordx4 v[220:223], v[134:135], off offset:128
	global_load_dwordx4 v[224:227], v[134:135], off offset:192
	s_nop 0
	v_lshl_add_u64 v[134:135], v[134:135], 0, vcc
	global_load_dwordx4 v[228:231], v[134:135], off
	global_load_dwordx4 v[232:235], v[134:135], off offset:64
	global_load_dwordx4 v[236:239], v[134:135], off offset:128
	global_load_dwordx4 v[240:243], v[134:135], off offset:192
	s_nop 0
	v_lshl_add_u64 v[134:135], v[134:135], 0, vcc
	s_waitcnt vmcnt(8)
	v_pk_fma_f32 v[124:125], v[124:125], v[140:141], v[156:157]
	v_pk_fma_f32 v[126:127], v[126:127], v[142:143], v[158:159]
	v_pk_fma_f32 v[120:121], v[120:121], v[144:145], v[160:161]
	v_pk_fma_f32 v[122:123], v[122:123], v[146:147], v[162:163]
	v_pk_fma_f32 v[116:117], v[116:117], v[148:149], v[164:165]
	v_pk_fma_f32 v[118:119], v[118:119], v[150:151], v[166:167]
	v_pk_fma_f32 v[112:113], v[112:113], v[152:153], v[168:169]
	v_pk_fma_f32 v[114:115], v[114:115], v[154:155], v[170:171]
	global_store_dwordx4 v[136:137], v[124:127], off
	global_store_dwordx4 v[136:137], v[120:123], off offset:64
	global_store_dwordx4 v[136:137], v[116:119], off offset:128
	global_store_dwordx4 v[136:137], v[112:115], off offset:192
	s_nop 0
	v_lshl_add_u64 v[136:137], v[136:137], 0, vcc
	global_load_dwordx4 v[156:159], v[134:135], off
	global_load_dwordx4 v[160:163], v[134:135], off offset:64
	global_load_dwordx4 v[164:167], v[134:135], off offset:128
	global_load_dwordx4 v[168:171], v[134:135], off offset:192
	s_nop 0
	v_lshl_add_u64 v[134:135], v[134:135], 0, vcc
	s_waitcnt vmcnt(12)
	v_pk_fma_f32 v[108:109], v[108:109], v[140:141], v[172:173]
	v_pk_fma_f32 v[110:111], v[110:111], v[142:143], v[174:175]
	v_pk_fma_f32 v[104:105], v[104:105], v[144:145], v[176:177]
	v_pk_fma_f32 v[106:107], v[106:107], v[146:147], v[178:179]
	v_pk_fma_f32 v[100:101], v[100:101], v[148:149], v[220:221]
	v_pk_fma_f32 v[102:103], v[102:103], v[150:151], v[222:223]
	v_pk_fma_f32 v[96:97], v[96:97], v[152:153], v[224:225]
	v_pk_fma_f32 v[98:99], v[98:99], v[154:155], v[226:227]
	global_store_dwordx4 v[136:137], v[108:111], off
	global_store_dwordx4 v[136:137], v[104:107], off offset:64
	global_store_dwordx4 v[136:137], v[100:103], off offset:128
	global_store_dwordx4 v[136:137], v[96:99], off offset:192
	s_nop 0
	v_lshl_add_u64 v[136:137], v[136:137], 0, vcc
	global_load_dwordx4 v[172:175], v[134:135], off
	global_load_dwordx4 v[176:179], v[134:135], off offset:64
	global_load_dwordx4 v[220:223], v[134:135], off offset:128
	global_load_dwordx4 v[224:227], v[134:135], off offset:192
	s_nop 0
	v_lshl_add_u64 v[134:135], v[134:135], 0, vcc
	s_waitcnt vmcnt(16)
	v_pk_fma_f32 v[92:93], v[92:93], v[140:141], v[228:229]
	v_pk_fma_f32 v[94:95], v[94:95], v[142:143], v[230:231]
	v_pk_fma_f32 v[88:89], v[88:89], v[144:145], v[232:233]
	v_pk_fma_f32 v[90:91], v[90:91], v[146:147], v[234:235]
	v_pk_fma_f32 v[84:85], v[84:85], v[148:149], v[236:237]
	v_pk_fma_f32 v[86:87], v[86:87], v[150:151], v[238:239]
	v_pk_fma_f32 v[80:81], v[80:81], v[152:153], v[240:241]
	v_pk_fma_f32 v[82:83], v[82:83], v[154:155], v[242:243]
	global_store_dwordx4 v[136:137], v[92:95], off
	global_store_dwordx4 v[136:137], v[88:91], off offset:64
	global_store_dwordx4 v[136:137], v[84:87], off offset:128
	global_store_dwordx4 v[136:137], v[80:83], off offset:192
	s_nop 0
	v_lshl_add_u64 v[136:137], v[136:137], 0, vcc
	global_load_dwordx4 v[228:231], v[134:135], off
	global_load_dwordx4 v[232:235], v[134:135], off offset:64
	global_load_dwordx4 v[236:239], v[134:135], off offset:128
	global_load_dwordx4 v[240:243], v[134:135], off offset:192
	s_nop 0
	v_lshl_add_u64 v[134:135], v[134:135], 0, vcc
	s_waitcnt vmcnt(16)
;     __device__ __forceinline__ void fin(int m, int n, f32x4 v, f32x4, f32x4) const { horiz(m, n, v); }
;     __device__ __forceinline__ void fin(int m, int n, f32x4 v, f32x4, f32x4) const { horiz(m, n, v); }
; template <int MI, bool SWAP, class Epi> ...
;     ...
;     if (SWAP) {
; #pragma unroll
;         for (int i2 = 0; i2 < MI / 2; ++i2) {
;             f32x4 pa[2][4], pg[2][4];
; #pragma unroll
;             for (int ii = 0; ii < 2; ++ii)
; #pragma unroll
;                 for (int j = 0; j < 4; ++j) epi.pre(m0 + wr * (MI * 16) + (i2 * 2 + ii) * 16 + fr, n0 + wc * 64 + j * 16 + fq * 4, pa[ii][j], pg[ii][j]);
;             __builtin_amdgcn_sched_barrier(0);
; #pragma unroll
;             for (int ii = 0; ii < 2; ++ii)
; #pragma unroll
;                 for (int j = 0; j < 4; ++j) epi.fin(m0 + wr * (MI * 16) + (i2 * 2 + ii) * 16 + fr, n0 + wc * 64 + j * 16 + fq * 4, acc[i2 * 2 + ii][j], pa[ii][j], pg[ii][j]);
;         }
	v_pk_fma_f32 v[76:77], v[76:77], v[140:141], v[156:157]
	v_pk_fma_f32 v[78:79], v[78:79], v[142:143], v[158:159]
	v_pk_fma_f32 v[72:73], v[72:73], v[144:145], v[160:161]
	v_pk_fma_f32 v[74:75], v[74:75], v[146:147], v[162:163]
	v_pk_fma_f32 v[68:69], v[68:69], v[148:149], v[164:165]
	v_pk_fma_f32 v[70:71], v[70:71], v[150:151], v[166:167]
	v_pk_fma_f32 v[64:65], v[64:65], v[152:153], v[168:169]
	v_pk_fma_f32 v[66:67], v[66:67], v[154:155], v[170:171]
	global_store_dwordx4 v[136:137], v[76:79], off
	global_store_dwordx4 v[136:137], v[72:75], off offset:64
	global_store_dwordx4 v[136:137], v[68:71], off offset:128
	global_store_dwordx4 v[136:137], v[64:67], off offset:192
	s_nop 0
	v_lshl_add_u64 v[136:137], v[136:137], 0, vcc
	global_load_dwordx4 v[156:159], v[134:135], off
	global_load_dwordx4 v[160:163], v[134:135], off offset:64
	global_load_dwordx4 v[164:167], v[134:135], off offset:128
	global_load_dwordx4 v[168:171], v[134:135], off offset:192
	s_nop 0
	v_lshl_add_u64 v[134:135], v[134:135], 0, vcc
	s_waitcnt vmcnt(16)
	v_pk_fma_f32 v[60:61], v[60:61], v[140:141], v[172:173]
	v_pk_fma_f32 v[62:63], v[62:63], v[142:143], v[174:175]
	v_pk_fma_f32 v[56:57], v[56:57], v[144:145], v[176:177]
	v_pk_fma_f32 v[58:59], v[58:59], v[146:147], v[178:179]
	v_pk_fma_f32 v[52:53], v[52:53], v[148:149], v[220:221]
	v_pk_fma_f32 v[54:55], v[54:55], v[150:151], v[222:223]
	v_pk_fma_f32 v[48:49], v[48:49], v[152:153], v[224:225]
	v_pk_fma_f32 v[50:51], v[50:51], v[154:155], v[226:227]
	global_store_dwordx4 v[136:137], v[60:63], off
	global_store_dwordx4 v[136:137], v[56:59], off offset:64
	global_store_dwordx4 v[136:137], v[52:55], off offset:128
	global_store_dwordx4 v[136:137], v[48:51], off offset:192
	s_nop 0
	v_lshl_add_u64 v[136:137], v[136:137], 0, vcc
	global_load_dwordx4 v[172:175], v[134:135], off
	global_load_dwordx4 v[176:179], v[134:135], off offset:64
	global_load_dwordx4 v[220:223], v[134:135], off offset:128
	global_load_dwordx4 v[224:227], v[134:135], off offset:192
	s_waitcnt vmcnt(16)
	v_pk_fma_f32 v[44:45], v[44:45], v[140:141], v[228:229]
	v_pk_fma_f32 v[46:47], v[46:47], v[142:143], v[230:231]
	v_pk_fma_f32 v[40:41], v[40:41], v[144:145], v[232:233]
	v_pk_fma_f32 v[42:43], v[42:43], v[146:147], v[234:235]
	v_pk_fma_f32 v[36:37], v[36:37], v[148:149], v[236:237]
	v_pk_fma_f32 v[38:39], v[38:39], v[150:151], v[238:239]
	v_pk_fma_f32 v[32:33], v[32:33], v[152:153], v[240:241]
	v_pk_fma_f32 v[34:35], v[34:35], v[154:155], v[242:243]
	global_store_dwordx4 v[136:137], v[44:47], off
	global_store_dwordx4 v[136:137], v[40:43], off offset:64
	global_store_dwordx4 v[136:137], v[36:39], off offset:128
	global_store_dwordx4 v[136:137], v[32:35], off offset:192
	s_nop 0
	v_lshl_add_u64 v[136:137], v[136:137], 0, vcc
	s_waitcnt vmcnt(12)
	v_pk_fma_f32 v[28:29], v[28:29], v[140:141], v[156:157]
	v_pk_fma_f32 v[30:31], v[30:31], v[142:143], v[158:159]
	v_pk_fma_f32 v[24:25], v[24:25], v[144:145], v[160:161]
	v_pk_fma_f32 v[26:27], v[26:27], v[146:147], v[162:163]
	v_pk_fma_f32 v[20:21], v[20:21], v[148:149], v[164:165]
	v_pk_fma_f32 v[22:23], v[22:23], v[150:151], v[166:167]
	v_pk_fma_f32 v[16:17], v[16:17], v[152:153], v[168:169]
	v_pk_fma_f32 v[18:19], v[18:19], v[154:155], v[170:171]
	global_store_dwordx4 v[136:137], v[28:31], off
	global_store_dwordx4 v[136:137], v[24:27], off offset:64
	global_store_dwordx4 v[136:137], v[20:23], off offset:128
	global_store_dwordx4 v[136:137], v[16:19], off offset:192
	s_nop 0
	v_lshl_add_u64 v[136:137], v[136:137], 0, vcc
	s_waitcnt vmcnt(8)
	v_pk_fma_f32 v[12:13], v[12:13], v[140:141], v[172:173]
	v_pk_fma_f32 v[14:15], v[14:15], v[142:143], v[174:175]
	v_pk_fma_f32 v[8:9], v[8:9], v[144:145], v[176:177]
	v_pk_fma_f32 v[10:11], v[10:11], v[146:147], v[178:179]
	v_pk_fma_f32 v[4:5], v[4:5], v[148:149], v[220:221]
	v_pk_fma_f32 v[6:7], v[6:7], v[150:151], v[222:223]
	v_pk_fma_f32 v[0:1], v[0:1], v[152:153], v[224:225]
	v_pk_fma_f32 v[2:3], v[2:3], v[154:155], v[226:227]
	global_store_dwordx4 v[136:137], v[12:15], off
	global_store_dwordx4 v[136:137], v[8:11], off offset:64
	global_store_dwordx4 v[136:137], v[4:7], off offset:128
	global_store_dwordx4 v[136:137], v[0:3], off offset:192
	s_andn2_b64 vcc, exec, s[2:3]
	s_mov_b64 s[24:25], -1
	s_cbranch_vccz .LBB0_2324
	s_mov_b32 s72, s10
	s_mov_b32 s70, s18
	s_branch .LBB0_2279
